# hand-written grid barrier: last XCD leader releases all XCC generation words directly (no TOPGEN relay), round counter in s100
# speedup vs baseline: 1.0102x; 1.0102x over previous
; #define LAS __attribute__((address_space(3)))
; __global__ void __launch_bounds__(NT, 2) hymba_fwd(Args args) {
;     extern __shared__ __attribute__((aligned(16))) unsigned char lds_raw[];
;     LAS unsigned char* lds = (LAS unsigned char*)lds_raw;
;     const int tid = threadIdx.x, lane = tid & 63, wave = __builtin_amdgcn_readfirstlane(tid >> 6);
;     const int G = gridDim.x, bx = blockIdx.x;
;     const int vcu = (G % 8 == 0) ? (bx % 8) * (G / 8) + bx / 8 : bx;
;     const int gw = vcu * NWAVES + wave, NGW = G * NWAVES;
;     unsigned char* ws = args.ws;
;     float* ssq = (float*)(ws + WS_SSQ);
;     const int lo = args.ph_lo, hi = args.ph_hi;
;     ...
;     unsigned fgen = 0;
;     ...
;     bf16* XB = (bf16*)(ws + WS_XB); bf16* Hb = (bf16*)(ws + WS_H);
;     if (lo < 0) cg::this_grid().sync();
;     volatile LAS unsigned* MISC = (volatile LAS unsigned*)(lds + MISC_OFF);
;     if (tid < 16) MISC[tid] = 0u;
;     __syncthreads();
;     XcdBarrier xbar = xcd_barrier_post((unsigned*)(ws + WS_BAR), MISC);
_Z9hymba_fwd4Args:
	s_mov_b32 s100, 0
	s_load_dword s3, s[0:1], 0xc0
	s_add_u32 s4, s0, 0xc0
	s_addc_u32 s5, s1, 0
	v_and_b32_e32 v209, 0x3ff, v0
	v_writelane_b32 v248, s4, 0
	v_readfirstlane_b32 s56, v209
	s_mov_b32 s60, s2
	v_writelane_b32 v248, s5, 1
	s_waitcnt lgkmcnt(0)
	s_and_b32 s4, s3, 7
	s_cmp_lg_u32 s4, 0
	s_cbranch_scc0 .LBB0_77
	s_load_dwordx4 s[48:51], s[0:1], 0xb0
	s_waitcnt lgkmcnt(0)
	s_cmp_gt_i32 s50, -1
	s_cbranch_scc0 .LBB0_78

; __device__ __forceinline__ unsigned xb_ld(unsigned* p)              { return __hip_atomic_load(p, __ATOMIC_RELAXED, __HIP_MEMORY_SCOPE_AGENT); }
; #define XB_SPIN(cond, bar) do { unsigned _sp = 0; while (cond) { __builtin_amdgcn_s_sleep(1); \
;     if ((++_sp & 255u) == 0u) { if (xb_ld(&(bar)[XB_TMO])) break; if (_sp > XB_SPIN_CAP) { atomicAdd(&(bar)[XB_TMO], 1u); break; } } } } while (0)
; __device__ __forceinline__ void xcd_barrier(const XcdBarrier& b) {
;     ...
;         } else {
;             XB_SPIN(xb_ld(&bar[XB_XGEN(b.x)]) == gen, bar);
;             __builtin_amdgcn_fence(__ATOMIC_ACQUIRE, "agent");
;             asm volatile("s_waitcnt vmcnt(0)" ::: "memory");
;         }
;     }
;     __syncthreads();
; }
.LBB0_130:
	s_or_b64 exec, exec, s[6:7]
	s_waitcnt lgkmcnt(0)
	s_barrier
	s_add_i32 s100, s100, 1

; __device__ __forceinline__ unsigned xb_ld(unsigned* p)              { return __hip_atomic_load(p, __ATOMIC_RELAXED, __HIP_MEMORY_SCOPE_AGENT); }
; __device__ __forceinline__ unsigned xb_add(unsigned* p, unsigned v) { return __hip_atomic_fetch_add(p, v, __ATOMIC_RELAXED, __HIP_MEMORY_SCOPE_AGENT); }
; #define XB_SPIN(cond, bar) do { unsigned _sp = 0; while (cond) { __builtin_amdgcn_s_sleep(1); \
;     if ((++_sp & 255u) == 0u) { if (xb_ld(&(bar)[XB_TMO])) break; if (_sp > XB_SPIN_CAP) { atomicAdd(&(bar)[XB_TMO], 1u); break; } } } } while (0)
; __device__ __forceinline__ void xcd_barrier(const XcdBarrier& b) {
;     asm volatile("s_waitcnt vmcnt(0)" ::: "memory");
;     __syncthreads();
;     if (threadIdx.x == 0) {
;         unsigned* bar = b.bar;
;         __builtin_amdgcn_s_waitcnt(0);
;         unsigned nloc = b.st[0], nx = b.st[1];
;         if (nloc == 0u) { xcd_barrier_complete(bar, b.x, nloc, nx); b.st[0] = nloc; b.st[1] = nx; }
;         const unsigned old = xb_add(&bar[XB_XSUB(b.x)], 1u);
;         const unsigned gen = old / nloc;
;         if (old + 1u == (gen + 1u) * nloc) {
;             __builtin_amdgcn_fence(__ATOMIC_RELEASE, "agent");
;             asm volatile("s_waitcnt vmcnt(0)" ::: "memory");
;             const unsigned og = xb_add(&bar[XB_TOP], 1u);
;             const unsigned tg = og / nx;
;             if (og + 1u == (tg + 1u) * nx) xb_add(&bar[XB_TOPGEN], 1u);
;             else XB_SPIN(xb_ld(&bar[XB_TOPGEN]) == tg, bar);
;             __builtin_amdgcn_fence(__ATOMIC_ACQUIRE, "agent");
;             xb_add(&bar[XB_XGEN(b.x)], 1u);
;             asm volatile("s_waitcnt vmcnt(0)" ::: "memory");
;         } else {
;             XB_SPIN(xb_ld(&bar[XB_XGEN(b.x)]) == gen, bar);
;             __builtin_amdgcn_fence(__ATOMIC_ACQUIRE, "agent");
;             asm volatile("s_waitcnt vmcnt(0)" ::: "memory");
;         }
;     }
;     __syncthreads();
; }
.LBB0_292:
	s_cmp_gt_i32 s51, 2
	s_cselect_b64 s[4:5], -1, 0
	s_and_b64 s[6:7], s[14:15], s[4:5]
	s_andn2_b64 vcc, exec, s[6:7]
	s_cbranch_vccnz .LBB0_346
	s_cmp_eq_u64 s[44:45], 0
	s_cbranch_scc1 .Lgb0_drain
	s_mov_b64 s[8:9], exec
	s_mov_b64 exec, s[44:45]
	s_lshl_b32 s10, s33, 8
	s_add_u32 s12, s46, s10
	s_addc_u32 s13, s47, 0
	v_mov_b32_e32 v0, 0x2400
	global_load_dword v5, v0, s[12:13] sc1
	s_mov_b64 exec, s[8:9]
.Lgb0_drain:
	s_waitcnt vmcnt(0) lgkmcnt(0)
	s_barrier
	s_cmp_eq_u64 s[44:45], 0
	s_cbranch_scc1 .Lgb0_end
	s_mov_b64 exec, s[44:45]
	s_mov_b32 s19, 0
	v_readfirstlane_b32 s14, v5
	s_cmp_ge_u32 s14, s100
	s_cbranch_scc1 .Lgb0_prev_ok
.Lgb0_prev:
	global_load_dword v5, v0, s[12:13] sc1
	s_waitcnt vmcnt(0)
	v_readfirstlane_b32 s14, v5
	s_cmp_ge_u32 s14, s100
	s_cbranch_scc1 .Lgb0_prev_ok
	s_sleep 1
	s_add_i32 s19, s19, 1
	s_cmp_lt_u32 s19, 20000
	s_cbranch_scc1 .Lgb0_prev
.Lgb0_prev_ok:
	v_mov_b32_e32 v1, 0x23fc0
	ds_read2_b32 v[2:3], v1 offset1:1
	v_mov_b32_e32 v0, 0x1400
	v_mov_b32_e32 v1, 1
	global_atomic_add v4, v0, v1, s[12:13] sc0
	s_add_i32 s17, s100, 1
	s_waitcnt vmcnt(0) lgkmcnt(0)
	v_readfirstlane_b32 s14, v4
	v_readfirstlane_b32 s15, v2
	v_readfirstlane_b32 s16, v3
	s_mul_i32 s18, s17, s15
	s_add_i32 s14, s14, 1
	s_cmp_lg_u32 s14, s18
	s_cbranch_scc1 .Lgb0_wait
	buffer_wbl2 sc1
	s_waitcnt vmcnt(0)
	v_mov_b32_e32 v0, 0x3400
	global_atomic_add v4, v0, v1, s[46:47] sc0
	s_mul_i32 s18, s17, s16
	s_waitcnt vmcnt(0)
	v_readfirstlane_b32 s14, v4
	s_add_i32 s14, s14, 1
	s_cmp_lg_u32 s14, s18
	s_cbranch_scc1 .Lgb0_wait
	v_mov_b32_e32 v0, 0x2400
	global_atomic_add v0, v1, s[46:47]
	global_atomic_add v0, v1, s[46:47] offset:256
	global_atomic_add v0, v1, s[46:47] offset:512
	global_atomic_add v0, v1, s[46:47] offset:768
	global_atomic_add v0, v1, s[46:47] offset:1024
	global_atomic_add v0, v1, s[46:47] offset:1280
	global_atomic_add v0, v1, s[46:47] offset:1536
	global_atomic_add v0, v1, s[46:47] offset:1792
	global_atomic_add v0, v1, s[46:47] offset:2048
	global_atomic_add v0, v1, s[46:47] offset:2304
	global_atomic_add v0, v1, s[46:47] offset:2560
	global_atomic_add v0, v1, s[46:47] offset:2816
	global_atomic_add v0, v1, s[46:47] offset:3072
	global_atomic_add v0, v1, s[46:47] offset:3328
	global_atomic_add v0, v1, s[46:47] offset:3584
	global_atomic_add v0, v1, s[46:47] offset:3840
	s_branch .Lgb0_acq
.Lgb0_wait:
	v_mov_b32_e32 v0, 0x2400
.Lgb0_poll:
	global_load_dword v4, v0, s[12:13] sc1
	s_waitcnt vmcnt(0)
	v_readfirstlane_b32 s14, v4
	s_cmp_ge_u32 s14, s17
	s_cbranch_scc1 .Lgb0_acq
	s_sleep 1
	s_add_i32 s19, s19, 1
	s_cmp_lt_u32 s19, 20000
	s_cbranch_scc1 .Lgb0_poll
.Lgb0_acq:
	buffer_inv sc1
	s_waitcnt vmcnt(0)
.Lgb0_done:
	s_mov_b64 exec, s[8:9]
.Lgb0_end:
	s_barrier
	s_add_i32 s100, s100, 1

; __device__ __forceinline__ void xcd_barrier(const XcdBarrier& b) {
;     asm volatile("s_waitcnt vmcnt(0)" ::: "memory");
;     __syncthreads();
.LBB0_392:
	s_cmp_gt_i32 s51, 3
	s_cselect_b64 s[4:5], -1, 0
	s_and_b64 s[6:7], s[10:11], s[4:5]
	s_andn2_b64 vcc, exec, s[6:7]
	s_cbranch_vccnz .LBB0_446
	s_cmp_eq_u64 s[44:45], 0
	s_cbranch_scc1 .Lgb1_drain
	s_mov_b64 s[8:9], exec
	s_mov_b64 exec, s[44:45]
	s_lshl_b32 s10, s33, 8
	s_add_u32 s12, s46, s10
	s_addc_u32 s13, s47, 0
	v_mov_b32_e32 v0, 0x2400
	global_load_dword v5, v0, s[12:13] sc1
	s_mov_b64 exec, s[8:9]

; __device__ __forceinline__ void xcd_barrier(const XcdBarrier& b) {
;     asm volatile("s_waitcnt vmcnt(0)" ::: "memory");
;     __syncthreads();
.LBB0_518:
	s_cmp_gt_i32 s51, 4
	s_cselect_b64 s[4:5], -1, 0
	s_and_b64 s[6:7], s[10:11], s[4:5]
	s_andn2_b64 vcc, exec, s[6:7]
	s_cbranch_vccnz .LBB0_572
	s_cmp_eq_u64 s[44:45], 0
	s_cbranch_scc1 .Lgb2_drain
	s_mov_b64 s[8:9], exec
	s_mov_b64 exec, s[44:45]
	s_lshl_b32 s10, s33, 8
	s_add_u32 s12, s46, s10
	s_addc_u32 s13, s47, 0
	v_mov_b32_e32 v0, 0x2400
	global_load_dword v5, v0, s[12:13] sc1
	s_mov_b64 exec, s[8:9]

; __device__ __forceinline__ void xcd_barrier(const XcdBarrier& b) {
;     asm volatile("s_waitcnt vmcnt(0)" ::: "memory");
;     __syncthreads();
.LBB0_689:
	s_cmp_gt_i32 s51, 5
	s_cselect_b64 s[4:5], -1, 0
	s_and_b64 s[6:7], s[14:15], s[4:5]
	s_andn2_b64 vcc, exec, s[6:7]
	s_cbranch_vccnz .LBB0_743
	s_cmp_eq_u64 s[44:45], 0
	s_cbranch_scc1 .Lgb3_drain
	s_mov_b64 s[8:9], exec
	s_mov_b64 exec, s[44:45]
	s_lshl_b32 s10, s33, 8
	s_add_u32 s12, s46, s10
	s_addc_u32 s13, s47, 0
	v_mov_b32_e32 v0, 0x2400
	global_load_dword v5, v0, s[12:13] sc1
	s_mov_b64 exec, s[8:9]

; __device__ __forceinline__ void xcd_barrier(const XcdBarrier& b) {
;     asm volatile("s_waitcnt vmcnt(0)" ::: "memory");
;     __syncthreads();
.LBB0_939:
	s_cmp_gt_u32 s51, 6
	s_cselect_b64 s[4:5], -1, 0
	s_and_b64 s[4:5], s[62:63], s[4:5]
	s_andn2_b64 vcc, exec, s[4:5]
	s_cbranch_vccnz .LBB0_993
	s_cmp_eq_u64 s[44:45], 0
	s_cbranch_scc1 .Lgb4_drain
	s_mov_b64 s[8:9], exec
	s_mov_b64 exec, s[44:45]
	s_lshl_b32 s10, s33, 8
	s_add_u32 s12, s46, s10
	s_addc_u32 s13, s47, 0
	v_mov_b32_e32 v0, 0x2400
	global_load_dword v5, v0, s[12:13] sc1
	s_mov_b64 exec, s[8:9]

; __device__ __forceinline__ void xcd_barrier(const XcdBarrier& b) {
;     asm volatile("s_waitcnt vmcnt(0)" ::: "memory");
;     __syncthreads();
.LBB0_1035:
	s_cmp_gt_i32 s51, 8
	s_cselect_b64 s[4:5], -1, 0
	s_and_b64 s[6:7], s[8:9], s[4:5]
	s_andn2_b64 vcc, exec, s[6:7]
	s_cbranch_vccnz .LBB0_1089
	s_cmp_eq_u64 s[44:45], 0
	s_cbranch_scc1 .Lgb5_drain
	s_mov_b64 s[8:9], exec
	s_mov_b64 exec, s[44:45]
	s_lshl_b32 s10, s33, 8
	s_add_u32 s12, s46, s10
	s_addc_u32 s13, s47, 0
	v_mov_b32_e32 v0, 0x2400
	global_load_dword v5, v0, s[12:13] sc1
	s_mov_b64 exec, s[8:9]

; __device__ __forceinline__ void xcd_barrier(const XcdBarrier& b) {
;     asm volatile("s_waitcnt vmcnt(0)" ::: "memory");
;     __syncthreads();
.LBB0_1111:
	s_cmp_gt_u32 s51, 9
	s_cselect_b64 s[4:5], -1, 0
	s_and_b64 s[4:5], s[8:9], s[4:5]
	s_andn2_b64 vcc, exec, s[4:5]
	s_cbranch_vccnz .LBB0_1165
	s_cmp_eq_u64 s[44:45], 0
	s_cbranch_scc1 .Lgb6_drain
	s_mov_b64 s[8:9], exec
	s_mov_b64 exec, s[44:45]
	s_lshl_b32 s10, s33, 8
	s_add_u32 s12, s46, s10
	s_addc_u32 s13, s47, 0
	v_mov_b32_e32 v0, 0x2400
	global_load_dword v5, v0, s[12:13] sc1
	s_mov_b64 exec, s[8:9]

; __device__ __forceinline__ void xcd_barrier(const XcdBarrier& b) {
;     asm volatile("s_waitcnt vmcnt(0)" ::: "memory");
;     __syncthreads();
.LBB0_1207:
	s_cmp_gt_i32 s51, 11
	s_cselect_b64 s[4:5], -1, 0
	s_and_b64 s[6:7], s[8:9], s[4:5]
	s_andn2_b64 vcc, exec, s[6:7]
	s_cbranch_vccnz .LBB0_1261
	s_cmp_eq_u64 s[44:45], 0
	s_cbranch_scc1 .Lgb7_drain
	s_mov_b64 s[8:9], exec
	s_mov_b64 exec, s[44:45]
	s_lshl_b32 s10, s33, 8
	s_add_u32 s12, s46, s10
	s_addc_u32 s13, s47, 0
	v_mov_b32_e32 v0, 0x2400
	global_load_dword v5, v0, s[12:13] sc1
	s_mov_b64 exec, s[8:9]

; __device__ __forceinline__ void xcd_barrier(const XcdBarrier& b) {
;     asm volatile("s_waitcnt vmcnt(0)" ::: "memory");
;     __syncthreads();
.LBB0_1356:
	s_cmp_gt_i32 s51, 12
	s_cselect_b64 s[4:5], -1, 0
	s_and_b64 s[6:7], s[14:15], s[4:5]
	s_andn2_b64 vcc, exec, s[6:7]
	s_cbranch_vccnz .LBB0_1410
	s_cmp_eq_u64 s[44:45], 0
	s_cbranch_scc1 .Lgb8_drain
	s_mov_b64 s[8:9], exec
	s_mov_b64 exec, s[44:45]
	s_lshl_b32 s10, s33, 8
	s_add_u32 s12, s46, s10
	s_addc_u32 s13, s47, 0
	v_mov_b32_e32 v0, 0x2400
	global_load_dword v5, v0, s[12:13] sc1
	s_mov_b64 exec, s[8:9]

; __global__ void __launch_bounds__(NT, 2) hymba_fwd(Args args) {
	.amdhsa_kernel _Z9hymba_fwd4Args
		.amdhsa_group_segment_fixed_size 0
		.amdhsa_private_segment_fixed_size 0
		.amdhsa_kernarg_size 448
		.amdhsa_user_sgpr_count 2
		.amdhsa_user_sgpr_dispatch_ptr 0
		.amdhsa_user_sgpr_queue_ptr 0
		.amdhsa_user_sgpr_kernarg_segment_ptr 1
		.amdhsa_user_sgpr_dispatch_id 0
		.amdhsa_user_sgpr_kernarg_preload_length 0
		.amdhsa_user_sgpr_kernarg_preload_offset 0
		.amdhsa_user_sgpr_private_segment_size 0
		.amdhsa_uses_dynamic_stack 0
		.amdhsa_enable_private_segment 0
		.amdhsa_system_sgpr_workgroup_id_x 1
		.amdhsa_system_sgpr_workgroup_id_y 0
		.amdhsa_system_sgpr_workgroup_id_z 0
		.amdhsa_system_sgpr_workgroup_info 0
		.amdhsa_system_vgpr_workitem_id 2
		.amdhsa_next_free_vgpr 249
		.amdhsa_next_free_sgpr 101
		.amdhsa_accum_offset 252
		.amdhsa_reserve_vcc 1
		.amdhsa_float_round_mode_32 0
		.amdhsa_float_round_mode_16_64 0
		.amdhsa_float_denorm_mode_32 3
		.amdhsa_float_denorm_mode_16_64 3
		.amdhsa_dx10_clamp 1
		.amdhsa_ieee_mode 1
		.amdhsa_fp16_overflow 0
		.amdhsa_tg_split 0
		.amdhsa_exception_fp_ieee_invalid_op 0
		.amdhsa_exception_fp_denorm_src 0
		.amdhsa_exception_fp_ieee_div_zero 0
		.amdhsa_exception_fp_ieee_overflow 0
		.amdhsa_exception_fp_ieee_underflow 0
		.amdhsa_exception_fp_ieee_inexact 0
		.amdhsa_exception_int_div_zero 0
	.end_amdhsa_kernel

; __global__ void __launch_bounds__(NT, 2) hymba_fwd(Args args) {
amdhsa.kernels:
  - .agpr_count:     0
    .args:
      - .offset:         0
        .size:           192
        .value_kind:     by_value
      - .offset:         192
        .size:           4
        .value_kind:     hidden_block_count_x
      - .offset:         196
        .size:           4
        .value_kind:     hidden_block_count_y
      - .offset:         200
        .size:           4
        .value_kind:     hidden_block_count_z
      - .offset:         204
        .size:           2
        .value_kind:     hidden_group_size_x
      - .offset:         206
        .size:           2
        .value_kind:     hidden_group_size_y
      - .offset:         208
        .size:           2
        .value_kind:     hidden_group_size_z
      - .offset:         210
        .size:           2
        .value_kind:     hidden_remainder_x
      - .offset:         212
        .size:           2
        .value_kind:     hidden_remainder_y
      - .offset:         214
        .size:           2
        .value_kind:     hidden_remainder_z
      - .offset:         232
        .size:           8
        .value_kind:     hidden_global_offset_x
      - .offset:         240
        .size:           8
        .value_kind:     hidden_global_offset_y
      - .offset:         248
        .size:           8
        .value_kind:     hidden_global_offset_z
      - .offset:         256
        .size:           2
        .value_kind:     hidden_grid_dims
      - .offset:         280
        .size:           8
        .value_kind:     hidden_multigrid_sync_arg
      - .offset:         312
        .size:           4
        .value_kind:     hidden_dynamic_lds_size
    .group_segment_fixed_size: 0
    .kernarg_segment_align: 8
    .kernarg_segment_size: 448
    .language:       OpenCL C
    .language_version:
      - 2
      - 0
    .max_flat_workgroup_size: 512
    .name:           _Z9hymba_fwd4Args
    .private_segment_fixed_size: 0
    .sgpr_count:     107
    .sgpr_spill_count: 7
    .symbol:         _Z9hymba_fwd4Args.kd
    .uniform_work_group_size: 1
    .uses_dynamic_stack: false
    .vgpr_count:     249
    .vgpr_spill_count: 0
    .wavefront_size: 64
